# fourth redundant phase-end s_barrier removed (down GEMM end; both seam paths re-wait and re-barrier)
# baseline (speedup 1.0000x reference)
; #define PG8_WAIT_V(n) asm volatile("s_waitcnt vmcnt(" #n ")" ::: "memory")
; #define PG8_BAR __builtin_amdgcn_s_barrier()
; template <class Epi, class Sched, bool ALIGN_EPI = false, bool SP2 = false, bool HALFM = false>
; __device__ __forceinline__ void gemm_phase(PG8_LAS unsigned char* lds, const Gemm g, const Sched& S, const Epi& E) {
;     ...
;     PG8_WAIT_V(0);
;     if constexpr (!ALIGN_EPI) { if (wr == 0) PG8_BAR; }
;     PG8_BAR;
.LBB0_322:
	s_waitcnt vmcnt(0)
	s_and_b64 vcc, exec, s[4:5]
	s_mov_b64 s[0:1], -1
	s_cbranch_vccnz .LBB0_263
